# out-proj (P3): next unit's residual-tile loads issued before the epilogue (into dead fragment registers) so they no longer queue behind the store tail; plus LDS-staged full-line epilogue stores
# baseline (speedup 1.0000x reference)
;     __device__ __forceinline__ void init(f32x4 (&acc)[2][2][4][2], const pg8::Unit& u, int ui, int wr, int wc, int fr, int fq) const {
;     ...
;                 for (int bj = 0; bj < 2; ++bj) { const u32x4 w = *(const u32x4*)(base + bj * 32);
;                     acc[ai][bj][m][0] = (f32x4){bf_lo(w.x), bf_hi(w.x), bf_lo(w.y), bf_hi(w.y)}; acc[ai][bj][m][1] = (f32x4){bf_lo(w.z), bf_hi(w.z), bf_lo(w.w), bf_hi(w.w)}; }
.LBB0_633:
	s_waitcnt vmcnt(24)
	v_lshlrev_b32_e32 v102, 16, v62
	v_and_b32_e32 v103, 0xffff0000, v62
	v_lshlrev_b32_e32 v104, 16, v63
	v_and_b32_e32 v105, 0xffff0000, v63
	v_lshlrev_b32_e32 v108, 16, v64
	v_and_b32_e32 v109, 0xffff0000, v64
	v_lshlrev_b32_e32 v110, 16, v65
	v_and_b32_e32 v111, 0xffff0000, v65
	v_lshlrev_b32_e32 v112, 16, v54
	v_and_b32_e32 v113, 0xffff0000, v54
	v_lshlrev_b32_e32 v54, 16, v55
	v_and_b32_e32 v55, 0xffff0000, v55
	v_lshlrev_b32_e32 v114, 16, v56
	v_and_b32_e32 v115, 0xffff0000, v56
	v_lshlrev_b32_e32 v56, 16, v57
	v_and_b32_e32 v57, 0xffff0000, v57
	v_lshlrev_b32_e32 v116, 16, v58
	v_and_b32_e32 v117, 0xffff0000, v58
	v_lshlrev_b32_e32 v118, 16, v59
	v_and_b32_e32 v119, 0xffff0000, v59
	v_lshlrev_b32_e32 v120, 16, v60
	v_and_b32_e32 v121, 0xffff0000, v60
	v_lshlrev_b32_e32 v122, 16, v61
	v_and_b32_e32 v123, 0xffff0000, v61
	v_lshlrev_b32_e32 v124, 16, v46
	v_and_b32_e32 v125, 0xffff0000, v46
	v_lshlrev_b32_e32 v126, 16, v47
	v_and_b32_e32 v127, 0xffff0000, v47
	v_lshlrev_b32_e32 v128, 16, v48
	v_and_b32_e32 v129, 0xffff0000, v48
	v_lshlrev_b32_e32 v158, 16, v49
	v_and_b32_e32 v159, 0xffff0000, v49
	v_lshlrev_b32_e32 v160, 16, v50
	v_and_b32_e32 v161, 0xffff0000, v50
	v_lshlrev_b32_e32 v162, 16, v51
	v_and_b32_e32 v163, 0xffff0000, v51
	v_lshlrev_b32_e32 v164, 16, v52
	v_and_b32_e32 v165, 0xffff0000, v52
	v_lshlrev_b32_e32 v166, 16, v53
	v_and_b32_e32 v167, 0xffff0000, v53
	v_lshlrev_b32_e32 v168, 16, v38
	v_and_b32_e32 v169, 0xffff0000, v38
	v_lshlrev_b32_e32 v170, 16, v39
	v_and_b32_e32 v171, 0xffff0000, v39
	v_lshlrev_b32_e32 v172, 16, v40
	v_and_b32_e32 v173, 0xffff0000, v40
	v_lshlrev_b32_e32 v174, 16, v41
	v_and_b32_e32 v175, 0xffff0000, v41
	v_lshlrev_b32_e32 v176, 16, v42
	v_and_b32_e32 v177, 0xffff0000, v42
	v_lshlrev_b32_e32 v178, 16, v43
	v_and_b32_e32 v179, 0xffff0000, v43
	v_lshlrev_b32_e32 v180, 16, v44
	v_and_b32_e32 v181, 0xffff0000, v44
	v_lshlrev_b32_e32 v182, 16, v45
	v_and_b32_e32 v183, 0xffff0000, v45
	v_lshlrev_b32_e32 v188, 16, v30
	v_and_b32_e32 v189, 0xffff0000, v30
	v_lshlrev_b32_e32 v194, 16, v31
	v_and_b32_e32 v195, 0xffff0000, v31
	v_lshlrev_b32_e32 v196, 16, v32
	v_and_b32_e32 v197, 0xffff0000, v32
	v_lshlrev_b32_e32 v198, 16, v33
	v_and_b32_e32 v199, 0xffff0000, v33
	v_lshlrev_b32_e32 v200, 16, v34
	v_and_b32_e32 v201, 0xffff0000, v34
	v_lshlrev_b32_e32 v202, 16, v35
	v_and_b32_e32 v203, 0xffff0000, v35
	v_lshlrev_b32_e32 v204, 16, v36
	v_and_b32_e32 v205, 0xffff0000, v36
	v_lshlrev_b32_e32 v206, 16, v37
	v_and_b32_e32 v207, 0xffff0000, v37
	v_lshlrev_b32_e32 v208, 16, v22
	v_and_b32_e32 v209, 0xffff0000, v22
	v_lshlrev_b32_e32 v210, 16, v23
	v_and_b32_e32 v211, 0xffff0000, v23
	v_lshlrev_b32_e32 v106, 16, v24
	v_and_b32_e32 v107, 0xffff0000, v24
	v_lshlrev_b32_e32 v212, 16, v25
	v_and_b32_e32 v213, 0xffff0000, v25
	v_lshlrev_b32_e32 v86, 16, v26
	v_and_b32_e32 v87, 0xffff0000, v26
	v_lshlrev_b32_e32 v88, 16, v27
	v_and_b32_e32 v89, 0xffff0000, v27
	v_lshlrev_b32_e32 v94, 16, v28
	v_and_b32_e32 v95, 0xffff0000, v28
	v_lshlrev_b32_e32 v96, 16, v29
	v_and_b32_e32 v97, 0xffff0000, v29
	v_lshlrev_b32_e32 v82, 16, v14
	v_and_b32_e32 v83, 0xffff0000, v14
	v_lshlrev_b32_e32 v152, 16, v15
	v_and_b32_e32 v153, 0xffff0000, v15
	v_lshlrev_b32_e32 v90, 16, v16
	v_and_b32_e32 v91, 0xffff0000, v16
	v_lshlrev_b32_e32 v92, 16, v17
	v_and_b32_e32 v93, 0xffff0000, v17
	v_lshlrev_b32_e32 v148, 16, v18
	v_and_b32_e32 v149, 0xffff0000, v18
	v_lshlrev_b32_e32 v72, 16, v19
	v_and_b32_e32 v73, 0xffff0000, v19
	v_lshlrev_b32_e32 v78, 16, v20
	v_and_b32_e32 v79, 0xffff0000, v20
	v_lshlrev_b32_e32 v80, 16, v21
	v_and_b32_e32 v81, 0xffff0000, v21
	v_lshlrev_b32_e32 v144, 16, v10
	v_and_b32_e32 v145, 0xffff0000, v10
	v_lshlrev_b32_e32 v146, 16, v11
	v_and_b32_e32 v147, 0xffff0000, v11
	v_lshlrev_b32_e32 v142, 16, v12
	v_and_b32_e32 v143, 0xffff0000, v12
	v_lshlrev_b32_e32 v76, 16, v13
	v_and_b32_e32 v77, 0xffff0000, v13
	v_lshlrev_b32_e32 v50, 16, v6
	v_and_b32_e32 v51, 0xffff0000, v6
	v_lshlrev_b32_e32 v52, 16, v7
	v_and_b32_e32 v53, 0xffff0000, v7
	v_lshlrev_b32_e32 v62, 16, v8
	v_and_b32_e32 v63, 0xffff0000, v8
	v_lshlrev_b32_e32 v64, 16, v9
	v_and_b32_e32 v65, 0xffff0000, v9
;     __device__ __forceinline__ void init(f32x4 (&acc)[2][2][4][2], const pg8::Unit& u, int ui, int wr, int wc, int fr, int fq) const {
;     ...
;                 for (int bj = 0; bj < 2; ++bj) { const u32x4 w = *(const u32x4*)(base + bj * 32);
;                     acc[ai][bj][m][0] = (f32x4){bf_lo(w.x), bf_hi(w.x), bf_lo(w.y), bf_hi(w.y)}; acc[ai][bj][m][1] = (f32x4){bf_lo(w.z), bf_hi(w.z), bf_lo(w.w), bf_hi(w.w)}; }
;             }
; #pragma unroll
;         for (int ai = 0; ai < 2; ++ai)
; #pragma unroll
;             for (int m = 0; m < 4; ++m) {
;                 const float ia = rl[ai * 128 + m * 16];
; #pragma unroll
;                 for (int bj = 0; bj < 2; ++bj)
; #pragma unroll
;                     for (int n = 0; n < 2; ++n) acc[ai][bj][m][n] = acc[ai][bj][m][n] * ia;
;             }
	v_lshlrev_b32_e32 v46, 16, v2
	v_and_b32_e32 v47, 0xffff0000, v2
	v_lshlrev_b32_e32 v48, 16, v3
	v_and_b32_e32 v49, 0xffff0000, v3
	v_lshlrev_b32_e32 v58, 16, v4
	v_and_b32_e32 v59, 0xffff0000, v4
	v_lshlrev_b32_e32 v60, 16, v5
	v_and_b32_e32 v61, 0xffff0000, v5
	v_pk_mul_f32 v[20:21], v[100:101], v[104:105] op_sel_hi:[0,1]
	v_pk_mul_f32 v[18:19], v[100:101], v[102:103] op_sel_hi:[0,1]
	v_pk_mul_f32 v[40:41], v[100:101], v[110:111] op_sel_hi:[0,1]
	v_pk_mul_f32 v[38:39], v[100:101], v[108:109] op_sel_hi:[0,1]
	v_pk_mul_f32 v[36:37], v[100:101], v[54:55] op_sel_hi:[0,1]
	v_pk_mul_f32 v[34:35], v[100:101], v[112:113] op_sel_hi:[0,1]
	v_pk_mul_f32 v[56:57], v[100:101], v[56:57] op_sel_hi:[0,1]
	v_pk_mul_f32 v[54:55], v[100:101], v[114:115] op_sel_hi:[0,1]
	v_pk_mul_f32 v[8:9], v[98:99], v[118:119] op_sel_hi:[0,1]
	v_pk_mul_f32 v[6:7], v[98:99], v[116:117] op_sel_hi:[0,1]
	v_pk_mul_f32 v[28:29], v[98:99], v[122:123] op_sel_hi:[0,1]
	v_pk_mul_f32 v[26:27], v[98:99], v[120:121] op_sel_hi:[0,1]
	v_pk_mul_f32 v[24:25], v[98:99], v[126:127] op_sel_hi:[0,1]
	v_pk_mul_f32 v[22:23], v[98:99], v[124:125] op_sel_hi:[0,1]
	v_pk_mul_f32 v[44:45], v[98:99], v[158:159] op_sel_hi:[0,1]
	v_pk_mul_f32 v[42:43], v[98:99], v[128:129] op_sel_hi:[0,1]
	v_pk_mul_f32 v[4:5], v[84:85], v[162:163] op_sel_hi:[0,1]
	v_pk_mul_f32 v[2:3], v[84:85], v[160:161] op_sel_hi:[0,1]
	v_pk_mul_f32 v[16:17], v[84:85], v[166:167] op_sel_hi:[0,1]
	v_pk_mul_f32 v[14:15], v[84:85], v[164:165] op_sel_hi:[0,1]
	v_pk_mul_f32 v[12:13], v[84:85], v[170:171] op_sel_hi:[0,1]
	v_pk_mul_f32 v[10:11], v[84:85], v[168:169] op_sel_hi:[0,1]
	v_pk_mul_f32 v[32:33], v[84:85], v[174:175] op_sel_hi:[0,1]
	v_pk_mul_f32 v[30:31], v[84:85], v[172:173] op_sel_hi:[0,1]
	v_pk_mul_f32 v[120:121], v[70:71], v[178:179] op_sel_hi:[0,1]
	v_pk_mul_f32 v[118:119], v[70:71], v[176:177] op_sel_hi:[0,1]
	v_pk_mul_f32 v[128:129], v[70:71], v[182:183] op_sel_hi:[0,1]
	v_pk_mul_f32 v[126:127], v[70:71], v[180:181] op_sel_hi:[0,1]
	v_pk_mul_f32 v[116:117], v[70:71], v[194:195] op_sel_hi:[0,1]
	v_pk_mul_f32 v[114:115], v[70:71], v[188:189] op_sel_hi:[0,1]
	v_pk_mul_f32 v[124:125], v[70:71], v[198:199] op_sel_hi:[0,1]
	v_pk_mul_f32 v[122:123], v[70:71], v[196:197] op_sel_hi:[0,1]
	v_pk_mul_f32 v[104:105], v[68:69], v[202:203] op_sel_hi:[0,1]
	v_pk_mul_f32 v[102:103], v[68:69], v[200:201] op_sel_hi:[0,1]
	v_pk_mul_f32 v[112:113], v[68:69], v[206:207] op_sel_hi:[0,1]
	v_pk_mul_f32 v[110:111], v[68:69], v[204:205] op_sel_hi:[0,1]
	v_pk_mul_f32 v[100:101], v[68:69], v[210:211] op_sel_hi:[0,1]
	v_pk_mul_f32 v[98:99], v[68:69], v[208:209] op_sel_hi:[0,1]
	v_pk_mul_f32 v[108:109], v[68:69], v[212:213] op_sel_hi:[0,1]
	v_pk_mul_f32 v[106:107], v[68:69], v[106:107] op_sel_hi:[0,1]
	v_pk_mul_f32 v[88:89], v[66:67], v[88:89] op_sel_hi:[0,1]
	v_pk_mul_f32 v[86:87], v[66:67], v[86:87] op_sel_hi:[0,1]
	v_pk_mul_f32 v[96:97], v[66:67], v[96:97] op_sel_hi:[0,1]
	v_pk_mul_f32 v[94:95], v[66:67], v[94:95] op_sel_hi:[0,1]
	v_pk_mul_f32 v[84:85], v[66:67], v[152:153] op_sel_hi:[0,1]
	v_pk_mul_f32 v[82:83], v[66:67], v[82:83] op_sel_hi:[0,1]
	v_pk_mul_f32 v[92:93], v[66:67], v[92:93] op_sel_hi:[0,1]
	v_pk_mul_f32 v[90:91], v[66:67], v[90:91] op_sel_hi:[0,1]
	v_pk_mul_f32 v[72:73], v[74:75], v[72:73] op_sel_hi:[0,1]
	v_pk_mul_f32 v[70:71], v[74:75], v[148:149] op_sel_hi:[0,1]
	v_pk_mul_f32 v[80:81], v[74:75], v[80:81] op_sel_hi:[0,1]
	v_pk_mul_f32 v[78:79], v[74:75], v[78:79] op_sel_hi:[0,1]
	v_pk_mul_f32 v[68:69], v[74:75], v[146:147] op_sel_hi:[0,1]
	v_pk_mul_f32 v[66:67], v[74:75], v[144:145] op_sel_hi:[0,1]
	v_pk_mul_f32 v[76:77], v[74:75], v[76:77] op_sel_hi:[0,1]
	v_pk_mul_f32 v[74:75], v[74:75], v[142:143] op_sel_hi:[0,1]
	v_pk_mul_f32 v[52:53], v[140:141], v[52:53] op_sel_hi:[0,1]
	v_pk_mul_f32 v[50:51], v[140:141], v[50:51] op_sel_hi:[0,1]
	v_pk_mul_f32 v[64:65], v[140:141], v[64:65] op_sel_hi:[0,1]
	v_pk_mul_f32 v[62:63], v[140:141], v[62:63] op_sel_hi:[0,1]
	v_pk_mul_f32 v[48:49], v[140:141], v[48:49] op_sel_hi:[0,1]
	v_pk_mul_f32 v[46:47], v[140:141], v[46:47] op_sel_hi:[0,1]
	v_pk_mul_f32 v[60:61], v[140:141], v[60:61] op_sel_hi:[0,1]
	v_pk_mul_f32 v[58:59], v[140:141], v[58:59] op_sel_hi:[0,1]
	s_mov_b64 s[14:15], 0

; #define LAS __attribute__((address_space(3)))
; __device__ __forceinline__ float fq_sum(float v) { v += __shfl_xor(v, 16); v += __shfl_xor(v, 32); return v; }
;     __device__ __forceinline__ void init(f32x4 (&acc)[2][2][4][2], const pg8::Unit& u, int ui, int wr, int wc, int fr, int fq) const {
;         int row0 = u.pm * 256 + wr * 64 + fr;
;         asm volatile("" : "+v"(row0));
;         const int col0 = u.pn * 256 + wc * 64 + 8 * fq;
;         const LAS float* rl = rows + ui * 768 + ((row0 - u.pm * 256));
; #pragma unroll
;         for (int ai = 0; ai < 2; ++ai)
; #pragma unroll
;             for (int m = 0; m < 4; ++m) {
;                 const int row = row0 + ai * 128 + m * 16;
;                 const bf16_t* base = xb + (size_t)row * DM + col0;
; #pragma unroll
;                 for (int bj = 0; bj < 2; ++bj) { const u32x4 w = *(const u32x4*)(base + bj * 32);
;                     acc[ai][bj][m][0] = (f32x4){bf_lo(w.x), bf_hi(w.x), bf_lo(w.y), bf_hi(w.y)}; acc[ai][bj][m][1] = (f32x4){bf_lo(w.z), bf_hi(w.z), bf_lo(w.w), bf_hi(w.w)}; }
;     __device__ __forceinline__ void operator()(const f32x4 (&acc)[2][2][4][2], const pg8::Unit& u, int ui, int wr, int wc, int fr, int fq) const {
;         const int row0 = u.pm * 256 + wr * 64 + fr;
;         const int col0 = u.pn * 256 + wc * 64 + 8 * fq;
;         const LAS float* rl = rows + ui * 768 + 512 + wr * 64 + fr;
; #pragma unroll
;         for (int ai = 0; ai < 2; ++ai)
; #pragma unroll
;             for (int m = 0; m < 4; ++m) {
;                 const int row = row0 + ai * 128 + m * 16;
;                 const float rb = rl[ai * 128 + m * 16];
;                 float* o = out + (size_t)row * DM + col0; bf16_t* xo = xb + (size_t)row * DM + col0;
;                 float ss = 0.f;
; #pragma unroll
;                 for (int bj = 0; bj < 2; ++bj) {
;                     const f32x4 v0 = acc[ai][bj][m][0] * rb, v1 = acc[ai][bj][m][1] * rb;
;                     if (last) { *(f32x4*)(o + bj * 32) = v0; *(f32x4*)(o + bj * 32 + 4) = v1; }
;                     else *(u32x4*)(xo + bj * 32) = pack8(v0, v1);
;                     ss += (v0[0] * v0[0] + v0[1] * v0[1]) + (v0[2] * v0[2] + v0[3] * v0[3]) + (v1[0] * v1[0] + v1[1] * v1[1]) + (v1[2] * v1[2] + v1[3] * v1[3]);
;                 }
;                 ss = fq_sum(ss);
;                 if (fq == 0) ssx[(size_t)row * 32 + u.pn * 4 + wc] = ss;
.LBB0_647:
	s_andn2_b64 vcc, exec, s[42:43]
	s_cbranch_vccnz .Lmy_p3_noinit
	s_lshl_b32 s9, s8, 8
	v_add_u32_e32 v164, s9, v154
	v_lshl_add_u32 v188, s0, 8, v193
	v_ashrrev_i32_e32 v165, 31, v164
	v_ashrrev_i32_e32 v189, 31, v188
	v_lshlrev_b64 v[164:165], 12, v[164:165]
	v_lshl_add_u64 v[164:165], s[54:55], 0, v[164:165]
	v_lshl_add_u64 v[188:189], v[188:189], 1, v[164:165]
	global_load_dwordx4 v[246:249], v[188:189], off
	global_load_dwordx4 v[238:241], v[188:189], off offset:64
	s_mov_b64 s[4:5], 0x10000
	v_lshl_add_u64 v[164:165], v[188:189], 0, s[4:5]
	global_load_dwordx4 v[242:245], v[164:165], off
	global_load_dwordx4 v[230:233], v[164:165], off offset:64
	s_mov_b64 s[4:5], 0x20000
	v_lshl_add_u64 v[164:165], v[188:189], 0, s[4:5]
	global_load_dwordx4 v[234:237], v[164:165], off
	global_load_dwordx4 v[222:225], v[164:165], off offset:64
	s_mov_b64 s[4:5], 0x30000
	v_lshl_add_u64 v[164:165], v[188:189], 0, s[4:5]
	global_load_dwordx4 v[226:229], v[164:165], off
	global_load_dwordx4 v[214:217], v[164:165], off offset:64
	s_mov_b64 s[4:5], 0x80000
	v_lshl_add_u64 v[164:165], v[188:189], 0, s[4:5]
	global_load_dwordx4 v[218:221], v[164:165], off
	global_load_dwordx4 v[206:209], v[164:165], off offset:64
	s_mov_b64 s[4:5], 0x90000
	v_lshl_add_u64 v[164:165], v[188:189], 0, s[4:5]
	global_load_dwordx4 v[210:213], v[164:165], off
	global_load_dwordx4 v[198:201], v[164:165], off offset:64
	s_mov_b64 s[4:5], 0xa0000
	v_lshl_add_u64 v[164:165], v[188:189], 0, s[4:5]
	global_load_dwordx4 v[202:205], v[164:165], off
	global_load_dwordx4 v[194:197], v[164:165], off offset:64
	s_mov_b64 s[4:5], 0xb0000
	v_lshl_add_u64 v[164:165], v[188:189], 0, s[4:5]
	global_load_dwordx4 v[180:183], v[164:165], off
	global_load_dwordx4 v[176:179], v[164:165], off offset:64
.Lmy_p3_noinit:
	s_mov_b64 s[4:5], 0x8000
	s_lshl_b32 s9, s81, 2
	s_add_i32 s1, s1, s9
	v_lshrrev_b32_e32 v168, 6, v193
	v_lshrrev_b32_e32 v169, 4, v154
	v_and_b32_e32 v169, 12, v169
	v_add_u32_e32 v168, v168, v169
	v_mul_u32_u24_e32 v168, 0x900, v168
	v_add_u32_e32 v168, 0x23000, v168
	v_lshrrev_b32_e32 v169, 4, v185
	v_lshrrev_b32_e32 v170, 3, v185
	v_and_b32_e32 v171, 7, v185
	v_lshlrev_b32_e32 v161, 7, v192
	v_lshl_add_u32 v161, v192, 4, v161
	v_lshl_add_u32 v161, v169, 4, v161
	v_add_u32_e32 v161, v161, v168
	v_lshlrev_b32_e32 v160, 7, v170
	v_lshl_add_u32 v160, v170, 4, v160
	v_lshl_add_u32 v160, v171, 4, v160
	v_add_u32_e32 v160, v160, v168
	v_sub_u32_e32 v172, v170, v192
	v_lshlrev_b32_e32 v172, 12, v172
	v_sub_u32_e32 v173, v171, v169
	v_lshl_add_u32 v162, v173, 4, v172
	v_ashrrev_i32_e32 v163, 31, v162
	v_lshl_add_u32 v146, v192, 2, s1
	ds_read_b32 v148, v146 offset:2048
	v_xor_b32_e32 v143, 16, v185
	v_cmp_lt_i32_e32 vcc, v143, v186
	v_lshl_add_u32 v142, s38, 8, v154
	v_lshl_add_u32 v140, s35, 8, v193
	s_waitcnt lgkmcnt(0)
	v_pk_mul_f32 v[20:21], v[20:21], v[148:149] op_sel_hi:[1,0]
	v_pk_mul_f32 v[158:159], v[18:19], v[148:149] op_sel_hi:[1,0]
	v_cvt_pk_bf16_f32 v19, v20, v21
	v_mul_f32_e32 v147, v159, v159
	v_mul_f32_e32 v21, v21, v21
	v_pk_mul_f32 v[38:39], v[38:39], v[148:149] op_sel_hi:[1,0]
	v_fmac_f32_e32 v147, v158, v158
	v_fmac_f32_e32 v21, v20, v20
	v_add_f32_e32 v20, v147, v21
	v_mul_f32_e32 v21, v39, v39
	v_pk_mul_f32 v[40:41], v[40:41], v[148:149] op_sel_hi:[1,0]
	v_fmac_f32_e32 v21, v38, v38
	v_add_f32_e32 v20, v21, v20
	v_mul_f32_e32 v21, v41, v41
	v_fmac_f32_e32 v21, v40, v40
	v_pk_mul_f32 v[36:37], v[36:37], v[148:149] op_sel_hi:[1,0]
	v_pk_mul_f32 v[34:35], v[34:35], v[148:149] op_sel_hi:[1,0]
	v_add_f32_e32 v20, v21, v20
	v_mul_f32_e32 v21, v35, v35
	v_mul_f32_e32 v147, v37, v37
	v_pk_mul_f32 v[54:55], v[54:55], v[148:149] op_sel_hi:[1,0]
	v_fmac_f32_e32 v21, v34, v34
	v_fmac_f32_e32 v147, v36, v36
	v_add_f32_e32 v21, v21, v147
	v_mul_f32_e32 v147, v55, v55
	v_pk_mul_f32 v[56:57], v[56:57], v[148:149] op_sel_hi:[1,0]
	v_fmac_f32_e32 v147, v54, v54
	v_add_f32_e32 v21, v147, v21
	v_mul_f32_e32 v147, v57, v57
	v_cndmask_b32_e32 v143, v185, v143, vcc
	v_fmac_f32_e32 v147, v56, v56
	v_lshlrev_b32_e32 v145, 2, v143
	v_xor_b32_e32 v143, 32, v185
	v_add_f32_e32 v21, v147, v21
	v_cmp_lt_i32_e32 vcc, v143, v186
	v_add_f32_e32 v147, v20, v21
	ds_bpermute_b32 v148, v145, v147
	v_cndmask_b32_e32 v143, v185, v143, vcc
	v_lshlrev_b32_e32 v144, 2, v143
	v_ashrrev_i32_e32 v143, 31, v142
	v_lshlrev_b64 v[152:153], 12, v[142:143]
	v_ashrrev_i32_e32 v141, 31, v140
	v_lshl_add_u64 v[152:153], s[54:55], 0, v[152:153]
	v_lshl_add_u64 v[152:153], v[140:141], 1, v[152:153]
	v_cvt_pk_bf16_f32 v18, v158, v159
	v_cvt_pk_bf16_f32 v20, v38, v39
	v_cvt_pk_bf16_f32 v21, v40, v41
	ds_write_b128 v161, v[18:21]
	s_lshl_b32 s14, s35, 2
	s_ashr_i32 s15, s14, 31
	s_waitcnt lgkmcnt(0)
	v_add_f32_e32 v18, v147, v148
	ds_bpermute_b32 v19, v144, v18
	v_cvt_pk_bf16_f32 v34, v34, v35
	v_cvt_pk_bf16_f32 v35, v36, v37
	v_cvt_pk_bf16_f32 v36, v54, v55
	v_cvt_pk_bf16_f32 v37, v56, v57
	ds_write_b128 v161, v[34:37] offset:64
	ds_read_b128 v[168:171], v160
	ds_read_b128 v[172:175], v160 offset:1152
	v_lshl_add_u64 v[166:167], v[152:153], 0, v[162:163]
	s_waitcnt lgkmcnt(0)
	global_store_dwordx4 v[166:167], v[168:171], off
	v_lshl_add_u64 v[166:167], v[166:167], 0, s[4:5]
	s_nop 0
	global_store_dwordx4 v[166:167], v[172:175], off
	s_and_saveexec_b64 s[16:17], s[40:41]
	v_readlane_b32 s51, v255, 9
	s_cbranch_execz .LBB0_649
	s_waitcnt lgkmcnt(0)
	v_add_f32_e32 v20, v18, v19
	v_lshlrev_b64 v[18:19], 7, v[142:143]
	v_lshl_add_u64 v[18:19], s[56:57], 0, v[18:19]
	v_lshl_add_u64 v[18:19], s[14:15], 2, v[18:19]
	s_lshl_b32 s44, s95, 2
	v_lshl_add_u64 v[18:19], v[18:19], 0, s[44:45]
	global_store_dword v[18:19], v20, off
; __device__ __forceinline__ float fq_sum(float v) { v += __shfl_xor(v, 16); v += __shfl_xor(v, 32); return v; }
; __device__ __forceinline__ u32x4 pack8(f32x4 a, f32x4 b) { u32x4 w; w.x = pk2(a[0], a[1]); w.y = pk2(a[2], a[3]); w.z = pk2(b[0], b[1]); w.w = pk2(b[2], b[3]); return w; }
;     __device__ __forceinline__ void operator()(const f32x4 (&acc)[2][2][4][2], const pg8::Unit& u, int ui, int wr, int wc, int fr, int fq) const {
;     ...
;                 const int row = row0 + ai * 128 + m * 16;
;                 const float rb = rl[ai * 128 + m * 16];
;                 float* o = out + (size_t)row * DM + col0; bf16_t* xo = xb + (size_t)row * DM + col0;
;                 float ss = 0.f;
; #pragma unroll
;                 for (int bj = 0; bj < 2; ++bj) {
;                     const f32x4 v0 = acc[ai][bj][m][0] * rb, v1 = acc[ai][bj][m][1] * rb;
;                     if (last) { *(f32x4*)(o + bj * 32) = v0; *(f32x4*)(o + bj * 32 + 4) = v1; }
;                     else *(u32x4*)(xo + bj * 32) = pack8(v0, v1);
;                     ss += (v0[0] * v0[0] + v0[1] * v0[1]) + (v0[2] * v0[2] + v0[3] * v0[3]) + (v1[0] * v1[0] + v1[1] * v1[1]) + (v1[2] * v1[2] + v1[3] * v1[3]);
;                 }
;                 ss = fq_sum(ss);
;                 if (fq == 0) ssx[(size_t)row * 32 + u.pn * 4 + wc] = ss;
.LBB0_649:
	s_or_b64 exec, exec, s[16:17]
	ds_read_b32 v20, v146 offset:2112
	v_or_b32_e32 v18, 16, v142
	s_waitcnt lgkmcnt(0)
	v_ashrrev_i32_e32 v19, 31, v18
	v_lshlrev_b64 v[34:35], 12, v[18:19]
	v_lshl_add_u64 v[34:35], s[54:55], 0, v[34:35]
	v_pk_mul_f32 v[8:9], v[8:9], v[20:21] op_sel_hi:[1,0]
	v_pk_mul_f32 v[36:37], v[6:7], v[20:21] op_sel_hi:[1,0]
	v_pk_mul_f32 v[28:29], v[28:29], v[20:21] op_sel_hi:[1,0]
	v_pk_mul_f32 v[26:27], v[26:27], v[20:21] op_sel_hi:[1,0]
	v_cvt_pk_bf16_f32 v7, v8, v9
	v_mul_f32_e32 v21, v37, v37
	v_mul_f32_e32 v9, v9, v9
	v_fmac_f32_e32 v21, v36, v36
	v_fmac_f32_e32 v9, v8, v8
	v_add_f32_e32 v8, v21, v9
	v_mul_f32_e32 v9, v27, v27
	v_fmac_f32_e32 v9, v26, v26
	v_add_f32_e32 v8, v9, v8
	v_mul_f32_e32 v9, v29, v29
	v_fmac_f32_e32 v9, v28, v28
	v_pk_mul_f32 v[24:25], v[24:25], v[20:21] op_sel_hi:[1,0]
	v_pk_mul_f32 v[22:23], v[22:23], v[20:21] op_sel_hi:[1,0]
	v_cvt_pk_bf16_f32 v6, v36, v37
	v_add_f32_e32 v8, v9, v8
	v_pk_mul_f32 v[36:37], v[44:45], v[20:21] op_sel_hi:[1,0]
	v_pk_mul_f32 v[38:39], v[42:43], v[20:21] op_sel_hi:[1,0]
	v_mul_f32_e32 v9, v23, v23
	v_mul_f32_e32 v20, v25, v25
	v_fmac_f32_e32 v9, v22, v22
	v_fmac_f32_e32 v20, v24, v24
	v_add_f32_e32 v9, v9, v20
	v_mul_f32_e32 v20, v39, v39
	v_fmac_f32_e32 v20, v38, v38
	v_add_f32_e32 v9, v20, v9
	v_mul_f32_e32 v20, v37, v37
	v_fmac_f32_e32 v20, v36, v36
	v_add_f32_e32 v9, v20, v9
	v_add_f32_e32 v21, v8, v9
	ds_bpermute_b32 v40, v145, v21
	v_lshl_add_u64 v[34:35], v[140:141], 1, v[34:35]
	v_cvt_pk_bf16_f32 v8, v26, v27
	v_cvt_pk_bf16_f32 v9, v28, v29
	ds_write_b128 v161, v[6:9]
	v_cvt_pk_bf16_f32 v20, v22, v23
	v_cvt_pk_bf16_f32 v22, v38, v39
	s_waitcnt lgkmcnt(0)
	v_add_f32_e32 v6, v21, v40
	ds_bpermute_b32 v7, v144, v6
	v_cvt_pk_bf16_f32 v21, v24, v25
	v_cvt_pk_bf16_f32 v23, v36, v37
	ds_write_b128 v161, v[20:23] offset:64
	ds_read_b128 v[168:171], v160
	ds_read_b128 v[172:175], v160 offset:1152
	v_lshl_add_u64 v[166:167], v[34:35], 0, v[162:163]
	s_waitcnt lgkmcnt(0)
	global_store_dwordx4 v[166:167], v[168:171], off
	v_lshl_add_u64 v[166:167], v[166:167], 0, s[4:5]
	s_nop 0
	global_store_dwordx4 v[166:167], v[172:175], off
	s_and_saveexec_b64 s[16:17], s[40:41]
	s_cbranch_execz .LBB0_651
	s_waitcnt lgkmcnt(0)
	v_add_f32_e32 v8, v6, v7
	v_lshlrev_b64 v[6:7], 7, v[18:19]
	v_lshl_add_u64 v[6:7], s[56:57], 0, v[6:7]
	v_lshl_add_u64 v[6:7], s[14:15], 2, v[6:7]
	s_lshl_b32 s44, s95, 2
	v_lshl_add_u64 v[6:7], v[6:7], 0, s[44:45]
	global_store_dword v[6:7], v8, off
.LBB0_651:
	s_or_b64 exec, exec, s[16:17]
	ds_read_b32 v8, v146 offset:2176
	v_or_b32_e32 v6, 32, v142
	s_waitcnt lgkmcnt(0)
	v_ashrrev_i32_e32 v7, 31, v6
	v_lshlrev_b64 v[18:19], 12, v[6:7]
	v_lshl_add_u64 v[18:19], s[54:55], 0, v[18:19]
	v_pk_mul_f32 v[4:5], v[4:5], v[8:9] op_sel_hi:[1,0]
	v_pk_mul_f32 v[20:21], v[2:3], v[8:9] op_sel_hi:[1,0]
	v_pk_mul_f32 v[16:17], v[16:17], v[8:9] op_sel_hi:[1,0]
	v_pk_mul_f32 v[14:15], v[14:15], v[8:9] op_sel_hi:[1,0]
	v_cvt_pk_bf16_f32 v3, v4, v5
	v_mul_f32_e32 v9, v21, v21
	v_mul_f32_e32 v5, v5, v5
	v_fmac_f32_e32 v9, v20, v20
	v_fmac_f32_e32 v5, v4, v4
	v_add_f32_e32 v4, v9, v5
	v_mul_f32_e32 v5, v15, v15
	v_fmac_f32_e32 v5, v14, v14
	v_add_f32_e32 v4, v5, v4
	v_mul_f32_e32 v5, v17, v17
	v_fmac_f32_e32 v5, v16, v16
	v_pk_mul_f32 v[12:13], v[12:13], v[8:9] op_sel_hi:[1,0]
	v_pk_mul_f32 v[10:11], v[10:11], v[8:9] op_sel_hi:[1,0]
	v_cvt_pk_bf16_f32 v2, v20, v21
	v_add_f32_e32 v4, v5, v4
	v_pk_mul_f32 v[20:21], v[32:33], v[8:9] op_sel_hi:[1,0]
	v_pk_mul_f32 v[22:23], v[30:31], v[8:9] op_sel_hi:[1,0]
	v_mul_f32_e32 v5, v11, v11
	v_mul_f32_e32 v8, v13, v13
	v_fmac_f32_e32 v5, v10, v10
	v_fmac_f32_e32 v8, v12, v12
	v_add_f32_e32 v5, v5, v8
	v_mul_f32_e32 v8, v23, v23
	v_fmac_f32_e32 v8, v22, v22
	v_add_f32_e32 v5, v8, v5
	v_mul_f32_e32 v8, v21, v21
	v_fmac_f32_e32 v8, v20, v20
	v_add_f32_e32 v5, v8, v5
	v_add_f32_e32 v9, v4, v5
	ds_bpermute_b32 v24, v145, v9
	v_lshl_add_u64 v[18:19], v[140:141], 1, v[18:19]
	v_cvt_pk_bf16_f32 v4, v14, v15
	v_cvt_pk_bf16_f32 v5, v16, v17
	ds_write_b128 v161, v[2:5]
	v_cvt_pk_bf16_f32 v8, v10, v11
	v_cvt_pk_bf16_f32 v10, v22, v23
	s_waitcnt lgkmcnt(0)
	v_add_f32_e32 v2, v9, v24
	ds_bpermute_b32 v3, v144, v2
	v_cvt_pk_bf16_f32 v9, v12, v13
	v_cvt_pk_bf16_f32 v11, v20, v21
	ds_write_b128 v161, v[8:11] offset:64
	ds_read_b128 v[168:171], v160
	ds_read_b128 v[172:175], v160 offset:1152
	v_lshl_add_u64 v[166:167], v[18:19], 0, v[162:163]
	s_waitcnt lgkmcnt(0)
	global_store_dwordx4 v[166:167], v[168:171], off
	v_lshl_add_u64 v[166:167], v[166:167], 0, s[4:5]
	s_nop 0
	global_store_dwordx4 v[166:167], v[172:175], off
	s_and_saveexec_b64 s[16:17], s[40:41]
	s_cbranch_execz .LBB0_653
	s_waitcnt lgkmcnt(0)
	v_add_f32_e32 v4, v2, v3
	v_lshlrev_b64 v[2:3], 7, v[6:7]
	v_lshl_add_u64 v[2:3], s[56:57], 0, v[2:3]
	v_lshl_add_u64 v[2:3], s[14:15], 2, v[2:3]
	s_lshl_b32 s44, s95, 2
	v_lshl_add_u64 v[2:3], v[2:3], 0, s[44:45]
	global_store_dword v[2:3], v4, off
; __device__ __forceinline__ float fq_sum(float v) { v += __shfl_xor(v, 16); v += __shfl_xor(v, 32); return v; }
; __device__ __forceinline__ u32x4 pack8(f32x4 a, f32x4 b) { u32x4 w; w.x = pk2(a[0], a[1]); w.y = pk2(a[2], a[3]); w.z = pk2(b[0], b[1]); w.w = pk2(b[2], b[3]); return w; }
;     __device__ __forceinline__ void operator()(const f32x4 (&acc)[2][2][4][2], const pg8::Unit& u, int ui, int wr, int wc, int fr, int fq) const {
;     ...
;                 const int row = row0 + ai * 128 + m * 16;
;                 const float rb = rl[ai * 128 + m * 16];
;                 float* o = out + (size_t)row * DM + col0; bf16_t* xo = xb + (size_t)row * DM + col0;
;                 float ss = 0.f;
; #pragma unroll
;                 for (int bj = 0; bj < 2; ++bj) {
;                     const f32x4 v0 = acc[ai][bj][m][0] * rb, v1 = acc[ai][bj][m][1] * rb;
;                     if (last) { *(f32x4*)(o + bj * 32) = v0; *(f32x4*)(o + bj * 32 + 4) = v1; }
;                     else *(u32x4*)(xo + bj * 32) = pack8(v0, v1);
;                     ss += (v0[0] * v0[0] + v0[1] * v0[1]) + (v0[2] * v0[2] + v0[3] * v0[3]) + (v1[0] * v1[0] + v1[1] * v1[1]) + (v1[2] * v1[2] + v1[3] * v1[3]);
;                 }
;                 ss = fq_sum(ss);
;                 if (fq == 0) ssx[(size_t)row * 32 + u.pn * 4 + wc] = ss;
.LBB0_653:
	s_or_b64 exec, exec, s[16:17]
	ds_read_b32 v6, v146 offset:2240
	v_or_b32_e32 v2, 48, v142
	s_waitcnt lgkmcnt(0)
	v_ashrrev_i32_e32 v3, 31, v2
	v_lshlrev_b64 v[4:5], 12, v[2:3]
	v_lshl_add_u64 v[4:5], s[54:55], 0, v[4:5]
	v_pk_mul_f32 v[8:9], v[120:121], v[6:7] op_sel_hi:[1,0]
	v_pk_mul_f32 v[12:13], v[118:119], v[6:7] op_sel_hi:[1,0]
	v_lshl_add_u64 v[10:11], v[140:141], 1, v[4:5]
	v_pk_mul_f32 v[14:15], v[128:129], v[6:7] op_sel_hi:[1,0]
	v_pk_mul_f32 v[16:17], v[126:127], v[6:7] op_sel_hi:[1,0]
	v_cvt_pk_bf16_f32 v5, v8, v9
	v_mul_f32_e32 v7, v13, v13
	v_mul_f32_e32 v9, v9, v9
	v_fmac_f32_e32 v7, v12, v12
	v_fmac_f32_e32 v9, v8, v8
	v_mul_f32_e32 v8, v17, v17
	v_add_f32_e32 v7, v7, v9
	v_fmac_f32_e32 v8, v16, v16
	v_add_f32_e32 v7, v8, v7
	v_mul_f32_e32 v8, v15, v15
	v_fmac_f32_e32 v8, v14, v14
	v_add_f32_e32 v7, v8, v7
	v_cvt_pk_bf16_f32 v4, v12, v13
	v_pk_mul_f32 v[8:9], v[116:117], v[6:7] op_sel_hi:[1,0]
	v_pk_mul_f32 v[12:13], v[114:115], v[6:7] op_sel_hi:[1,0]
	v_pk_mul_f32 v[18:19], v[124:125], v[6:7] op_sel_hi:[1,0]
	v_pk_mul_f32 v[20:21], v[122:123], v[6:7] op_sel_hi:[1,0]
	v_mul_f32_e32 v6, v13, v13
	v_mul_f32_e32 v22, v9, v9
	v_fmac_f32_e32 v6, v12, v12
	v_fmac_f32_e32 v22, v8, v8
	v_add_f32_e32 v6, v6, v22
	v_mul_f32_e32 v22, v21, v21
	v_fmac_f32_e32 v22, v20, v20
	v_add_f32_e32 v6, v22, v6
	v_mul_f32_e32 v22, v19, v19
	v_fmac_f32_e32 v22, v18, v18
	v_add_f32_e32 v6, v22, v6
	v_add_f32_e32 v22, v7, v6
	ds_bpermute_b32 v23, v145, v22
	v_cvt_pk_bf16_f32 v6, v16, v17
	v_cvt_pk_bf16_f32 v7, v14, v15
	ds_write_b128 v161, v[4:7]
	s_waitcnt lgkmcnt(0)
	s_nop 0
	v_add_f32_e32 v4, v22, v23
	ds_bpermute_b32 v5, v144, v4
	v_cvt_pk_bf16_f32 v6, v12, v13
	v_cvt_pk_bf16_f32 v7, v8, v9
	v_cvt_pk_bf16_f32 v8, v20, v21
	v_cvt_pk_bf16_f32 v9, v18, v19
	ds_write_b128 v161, v[6:9] offset:64
	ds_read_b128 v[168:171], v160
	ds_read_b128 v[172:175], v160 offset:1152
	v_lshl_add_u64 v[166:167], v[10:11], 0, v[162:163]
	s_waitcnt lgkmcnt(0)
	global_store_dwordx4 v[166:167], v[168:171], off
	v_lshl_add_u64 v[166:167], v[166:167], 0, s[4:5]
	s_nop 0
	global_store_dwordx4 v[166:167], v[172:175], off
	s_and_saveexec_b64 s[16:17], s[40:41]
	s_cbranch_execz .LBB0_655
	v_lshlrev_b64 v[2:3], 7, v[2:3]
	v_lshl_add_u64 v[2:3], s[56:57], 0, v[2:3]
	v_lshl_add_u64 v[2:3], s[14:15], 2, v[2:3]
	s_lshl_b32 s44, s95, 2
	s_waitcnt lgkmcnt(0)
	v_add_f32_e32 v4, v4, v5
	v_lshl_add_u64 v[2:3], v[2:3], 0, s[44:45]
	global_store_dword v[2:3], v4, off
.LBB0_655:
	s_or_b64 exec, exec, s[16:17]
	ds_read_b32 v6, v146 offset:2560
	v_add_u32_e32 v2, 0x80, v142
	v_ashrrev_i32_e32 v3, 31, v2
	s_waitcnt lgkmcnt(0)
	v_lshlrev_b64 v[4:5], 12, v[2:3]
	v_lshl_add_u64 v[4:5], s[54:55], 0, v[4:5]
	v_pk_mul_f32 v[8:9], v[104:105], v[6:7] op_sel_hi:[1,0]
	v_pk_mul_f32 v[12:13], v[102:103], v[6:7] op_sel_hi:[1,0]
	v_lshl_add_u64 v[10:11], v[140:141], 1, v[4:5]
	v_pk_mul_f32 v[14:15], v[112:113], v[6:7] op_sel_hi:[1,0]
	v_pk_mul_f32 v[16:17], v[110:111], v[6:7] op_sel_hi:[1,0]
	v_cvt_pk_bf16_f32 v5, v8, v9
	v_mul_f32_e32 v7, v13, v13
	v_mul_f32_e32 v9, v9, v9
	v_fmac_f32_e32 v7, v12, v12
	v_fmac_f32_e32 v9, v8, v8
	v_mul_f32_e32 v8, v17, v17
	v_add_f32_e32 v7, v7, v9
	v_fmac_f32_e32 v8, v16, v16
	v_add_f32_e32 v7, v8, v7
	v_mul_f32_e32 v8, v15, v15
	v_fmac_f32_e32 v8, v14, v14
	v_add_f32_e32 v7, v8, v7
	v_cvt_pk_bf16_f32 v4, v12, v13
	v_pk_mul_f32 v[8:9], v[100:101], v[6:7] op_sel_hi:[1,0]
	v_pk_mul_f32 v[12:13], v[98:99], v[6:7] op_sel_hi:[1,0]
	v_pk_mul_f32 v[18:19], v[108:109], v[6:7] op_sel_hi:[1,0]
	v_pk_mul_f32 v[20:21], v[106:107], v[6:7] op_sel_hi:[1,0]
	v_mul_f32_e32 v6, v13, v13
	v_mul_f32_e32 v22, v9, v9
	v_fmac_f32_e32 v6, v12, v12
	v_fmac_f32_e32 v22, v8, v8
	v_add_f32_e32 v6, v6, v22
	v_mul_f32_e32 v22, v21, v21
	v_fmac_f32_e32 v22, v20, v20
	v_add_f32_e32 v6, v22, v6
	v_mul_f32_e32 v22, v19, v19
	v_fmac_f32_e32 v22, v18, v18
	v_add_f32_e32 v6, v22, v6
	v_add_f32_e32 v22, v7, v6
	ds_bpermute_b32 v23, v145, v22
	v_cvt_pk_bf16_f32 v6, v16, v17
	v_cvt_pk_bf16_f32 v7, v14, v15
	ds_write_b128 v161, v[4:7]
	s_waitcnt lgkmcnt(0)
	s_nop 0
	v_add_f32_e32 v4, v22, v23
	ds_bpermute_b32 v5, v144, v4
	v_cvt_pk_bf16_f32 v6, v12, v13
	v_cvt_pk_bf16_f32 v7, v8, v9
	v_cvt_pk_bf16_f32 v8, v20, v21
	v_cvt_pk_bf16_f32 v9, v18, v19
	ds_write_b128 v161, v[6:9] offset:64
	ds_read_b128 v[168:171], v160
	ds_read_b128 v[172:175], v160 offset:1152
	v_lshl_add_u64 v[166:167], v[10:11], 0, v[162:163]
	s_waitcnt lgkmcnt(0)
	global_store_dwordx4 v[166:167], v[168:171], off
	v_lshl_add_u64 v[166:167], v[166:167], 0, s[4:5]
	s_nop 0
	global_store_dwordx4 v[166:167], v[172:175], off
	s_and_saveexec_b64 s[16:17], s[40:41]
	s_cbranch_execz .LBB0_657
	v_lshlrev_b64 v[2:3], 7, v[2:3]
	v_lshl_add_u64 v[2:3], s[56:57], 0, v[2:3]
	v_lshl_add_u64 v[2:3], s[14:15], 2, v[2:3]
	s_lshl_b32 s44, s95, 2
	s_waitcnt lgkmcnt(0)
	v_add_f32_e32 v4, v4, v5
	v_lshl_add_u64 v[2:3], v[2:3], 0, s[44:45]
	global_store_dword v[2:3], v4, off
; __device__ __forceinline__ float fq_sum(float v) { v += __shfl_xor(v, 16); v += __shfl_xor(v, 32); return v; }
; __device__ __forceinline__ u32x4 pack8(f32x4 a, f32x4 b) { u32x4 w; w.x = pk2(a[0], a[1]); w.y = pk2(a[2], a[3]); w.z = pk2(b[0], b[1]); w.w = pk2(b[2], b[3]); return w; }
;     __device__ __forceinline__ void operator()(const f32x4 (&acc)[2][2][4][2], const pg8::Unit& u, int ui, int wr, int wc, int fr, int fq) const {
;     ...
;                 const int row = row0 + ai * 128 + m * 16;
;                 const float rb = rl[ai * 128 + m * 16];
;                 float* o = out + (size_t)row * DM + col0; bf16_t* xo = xb + (size_t)row * DM + col0;
;                 float ss = 0.f;
; #pragma unroll
;                 for (int bj = 0; bj < 2; ++bj) {
;                     const f32x4 v0 = acc[ai][bj][m][0] * rb, v1 = acc[ai][bj][m][1] * rb;
;                     if (last) { *(f32x4*)(o + bj * 32) = v0; *(f32x4*)(o + bj * 32 + 4) = v1; }
;                     else *(u32x4*)(xo + bj * 32) = pack8(v0, v1);
;                     ss += (v0[0] * v0[0] + v0[1] * v0[1]) + (v0[2] * v0[2] + v0[3] * v0[3]) + (v1[0] * v1[0] + v1[1] * v1[1]) + (v1[2] * v1[2] + v1[3] * v1[3]);
;                 }
;                 ss = fq_sum(ss);
;                 if (fq == 0) ssx[(size_t)row * 32 + u.pn * 4 + wc] = ss;
.LBB0_657:
	s_or_b64 exec, exec, s[16:17]
	ds_read_b32 v6, v146 offset:2624
	v_add_u32_e32 v2, 0x90, v142
	v_ashrrev_i32_e32 v3, 31, v2
	s_waitcnt lgkmcnt(0)
	v_lshlrev_b64 v[4:5], 12, v[2:3]
	v_lshl_add_u64 v[4:5], s[54:55], 0, v[4:5]
	v_pk_mul_f32 v[8:9], v[88:89], v[6:7] op_sel_hi:[1,0]
	v_pk_mul_f32 v[12:13], v[86:87], v[6:7] op_sel_hi:[1,0]
	v_lshl_add_u64 v[10:11], v[140:141], 1, v[4:5]
	v_pk_mul_f32 v[14:15], v[96:97], v[6:7] op_sel_hi:[1,0]
	v_pk_mul_f32 v[16:17], v[94:95], v[6:7] op_sel_hi:[1,0]
	v_cvt_pk_bf16_f32 v5, v8, v9
	v_mul_f32_e32 v7, v13, v13
	v_mul_f32_e32 v9, v9, v9
	v_fmac_f32_e32 v7, v12, v12
	v_fmac_f32_e32 v9, v8, v8
	v_mul_f32_e32 v8, v17, v17
	v_add_f32_e32 v7, v7, v9
	v_fmac_f32_e32 v8, v16, v16
	v_add_f32_e32 v7, v8, v7
	v_mul_f32_e32 v8, v15, v15
	v_fmac_f32_e32 v8, v14, v14
	v_add_f32_e32 v7, v8, v7
	v_cvt_pk_bf16_f32 v4, v12, v13
	v_pk_mul_f32 v[8:9], v[84:85], v[6:7] op_sel_hi:[1,0]
	v_pk_mul_f32 v[12:13], v[82:83], v[6:7] op_sel_hi:[1,0]
	v_pk_mul_f32 v[18:19], v[92:93], v[6:7] op_sel_hi:[1,0]
	v_pk_mul_f32 v[20:21], v[90:91], v[6:7] op_sel_hi:[1,0]
	v_mul_f32_e32 v6, v13, v13
	v_mul_f32_e32 v22, v9, v9
	v_fmac_f32_e32 v6, v12, v12
	v_fmac_f32_e32 v22, v8, v8
	v_add_f32_e32 v6, v6, v22
	v_mul_f32_e32 v22, v21, v21
	v_fmac_f32_e32 v22, v20, v20
	v_add_f32_e32 v6, v22, v6
	v_mul_f32_e32 v22, v19, v19
	v_fmac_f32_e32 v22, v18, v18
	v_add_f32_e32 v6, v22, v6
	v_add_f32_e32 v22, v7, v6
	ds_bpermute_b32 v23, v145, v22
	v_cvt_pk_bf16_f32 v6, v16, v17
	v_cvt_pk_bf16_f32 v7, v14, v15
	ds_write_b128 v161, v[4:7]
	s_waitcnt lgkmcnt(0)
	s_nop 0
	v_add_f32_e32 v4, v22, v23
	ds_bpermute_b32 v5, v144, v4
	v_cvt_pk_bf16_f32 v6, v12, v13
	v_cvt_pk_bf16_f32 v7, v8, v9
	v_cvt_pk_bf16_f32 v8, v20, v21
	v_cvt_pk_bf16_f32 v9, v18, v19
	ds_write_b128 v161, v[6:9] offset:64
	ds_read_b128 v[168:171], v160
	ds_read_b128 v[172:175], v160 offset:1152
	v_lshl_add_u64 v[166:167], v[10:11], 0, v[162:163]
	s_waitcnt lgkmcnt(0)
	global_store_dwordx4 v[166:167], v[168:171], off
	v_lshl_add_u64 v[166:167], v[166:167], 0, s[4:5]
	s_nop 0
	global_store_dwordx4 v[166:167], v[172:175], off
	s_and_saveexec_b64 s[16:17], s[40:41]
	s_cbranch_execz .LBB0_659
	v_lshlrev_b64 v[2:3], 7, v[2:3]
	v_lshl_add_u64 v[2:3], s[56:57], 0, v[2:3]
	v_lshl_add_u64 v[2:3], s[14:15], 2, v[2:3]
	s_lshl_b32 s44, s95, 2
	s_waitcnt lgkmcnt(0)
	v_add_f32_e32 v4, v4, v5
	v_lshl_add_u64 v[2:3], v[2:3], 0, s[44:45]
	global_store_dword v[2:3], v4, off
.LBB0_659:
	s_or_b64 exec, exec, s[16:17]
	ds_read_b32 v6, v146 offset:2688
	v_add_u32_e32 v2, 0xa0, v142
	v_ashrrev_i32_e32 v3, 31, v2
	s_waitcnt lgkmcnt(0)
	v_lshlrev_b64 v[4:5], 12, v[2:3]
	v_lshl_add_u64 v[4:5], s[54:55], 0, v[4:5]
	v_pk_mul_f32 v[8:9], v[72:73], v[6:7] op_sel_hi:[1,0]
	v_pk_mul_f32 v[12:13], v[70:71], v[6:7] op_sel_hi:[1,0]
	v_lshl_add_u64 v[10:11], v[140:141], 1, v[4:5]
	v_pk_mul_f32 v[14:15], v[80:81], v[6:7] op_sel_hi:[1,0]
	v_pk_mul_f32 v[16:17], v[78:79], v[6:7] op_sel_hi:[1,0]
	v_cvt_pk_bf16_f32 v5, v8, v9
	v_mul_f32_e32 v7, v13, v13
	v_mul_f32_e32 v9, v9, v9
	v_fmac_f32_e32 v7, v12, v12
	v_fmac_f32_e32 v9, v8, v8
	v_mul_f32_e32 v8, v17, v17
	v_add_f32_e32 v7, v7, v9
	v_fmac_f32_e32 v8, v16, v16
	v_add_f32_e32 v7, v8, v7
	v_mul_f32_e32 v8, v15, v15
	v_fmac_f32_e32 v8, v14, v14
	v_add_f32_e32 v7, v8, v7
	v_cvt_pk_bf16_f32 v4, v12, v13
	v_pk_mul_f32 v[8:9], v[68:69], v[6:7] op_sel_hi:[1,0]
	v_pk_mul_f32 v[12:13], v[66:67], v[6:7] op_sel_hi:[1,0]
	v_pk_mul_f32 v[18:19], v[76:77], v[6:7] op_sel_hi:[1,0]
	v_pk_mul_f32 v[20:21], v[74:75], v[6:7] op_sel_hi:[1,0]
	v_mul_f32_e32 v6, v13, v13
	v_mul_f32_e32 v22, v9, v9
	v_fmac_f32_e32 v6, v12, v12
	v_fmac_f32_e32 v22, v8, v8
	v_add_f32_e32 v6, v6, v22
	v_mul_f32_e32 v22, v21, v21
	v_fmac_f32_e32 v22, v20, v20
	v_add_f32_e32 v6, v22, v6
	v_mul_f32_e32 v22, v19, v19
	v_fmac_f32_e32 v22, v18, v18
	v_add_f32_e32 v6, v22, v6
	v_add_f32_e32 v22, v7, v6
	ds_bpermute_b32 v23, v145, v22
	v_cvt_pk_bf16_f32 v6, v16, v17
	v_cvt_pk_bf16_f32 v7, v14, v15
	ds_write_b128 v161, v[4:7]
	s_waitcnt lgkmcnt(0)
	s_nop 0
	v_add_f32_e32 v4, v22, v23
	ds_bpermute_b32 v5, v144, v4
	v_cvt_pk_bf16_f32 v6, v12, v13
	v_cvt_pk_bf16_f32 v7, v8, v9
	v_cvt_pk_bf16_f32 v8, v20, v21
	v_cvt_pk_bf16_f32 v9, v18, v19
	ds_write_b128 v161, v[6:9] offset:64
	ds_read_b128 v[168:171], v160
	ds_read_b128 v[172:175], v160 offset:1152
	v_lshl_add_u64 v[166:167], v[10:11], 0, v[162:163]
	s_waitcnt lgkmcnt(0)
	global_store_dwordx4 v[166:167], v[168:171], off
	v_lshl_add_u64 v[166:167], v[166:167], 0, s[4:5]
	s_nop 0
	global_store_dwordx4 v[166:167], v[172:175], off
	s_and_saveexec_b64 s[16:17], s[40:41]
	s_cbranch_execz .LBB0_661
	v_lshlrev_b64 v[2:3], 7, v[2:3]
	v_lshl_add_u64 v[2:3], s[56:57], 0, v[2:3]
	v_lshl_add_u64 v[2:3], s[14:15], 2, v[2:3]
	s_lshl_b32 s44, s95, 2
	s_waitcnt lgkmcnt(0)
	v_add_f32_e32 v4, v4, v5
	v_lshl_add_u64 v[2:3], v[2:3], 0, s[44:45]
	global_store_dword v[2:3], v4, off
; #define LAS __attribute__((address_space(3)))
; __device__ __forceinline__ float fq_sum(float v) { v += __shfl_xor(v, 16); v += __shfl_xor(v, 32); return v; }
;     __device__ __forceinline__ void init(f32x4 (&acc)[2][2][4][2], const pg8::Unit& u, int ui, int wr, int wc, int fr, int fq) const {
;         int row0 = u.pm * 256 + wr * 64 + fr;
;         asm volatile("" : "+v"(row0));
;         const int col0 = u.pn * 256 + wc * 64 + 8 * fq;
;         const LAS float* rl = rows + ui * 768 + ((row0 - u.pm * 256));
; #pragma unroll
;         for (int ai = 0; ai < 2; ++ai)
; #pragma unroll
;             for (int m = 0; m < 4; ++m) {
;                 const int row = row0 + ai * 128 + m * 16;
;                 const bf16_t* base = xb + (size_t)row * DM + col0;
; #pragma unroll
;                 for (int bj = 0; bj < 2; ++bj) { const u32x4 w = *(const u32x4*)(base + bj * 32);
;                     acc[ai][bj][m][0] = (f32x4){bf_lo(w.x), bf_hi(w.x), bf_lo(w.y), bf_hi(w.y)}; acc[ai][bj][m][1] = (f32x4){bf_lo(w.z), bf_hi(w.z), bf_lo(w.w), bf_hi(w.w)}; }
;             }
; #pragma unroll
;         for (int ai = 0; ai < 2; ++ai)
; #pragma unroll
;             for (int m = 0; m < 4; ++m) {
;                 const float ia = rl[ai * 128 + m * 16];
;     __device__ __forceinline__ void operator()(const f32x4 (&acc)[2][2][4][2], const pg8::Unit& u, int ui, int wr, int wc, int fr, int fq) const {
;     ...
;                 const int row = row0 + ai * 128 + m * 16;
;                 const float rb = rl[ai * 128 + m * 16];
;                 float* o = out + (size_t)row * DM + col0; bf16_t* xo = xb + (size_t)row * DM + col0;
;                 float ss = 0.f;
; #pragma unroll
;                 for (int bj = 0; bj < 2; ++bj) {
;                     const f32x4 v0 = acc[ai][bj][m][0] * rb, v1 = acc[ai][bj][m][1] * rb;
;                     if (last) { *(f32x4*)(o + bj * 32) = v0; *(f32x4*)(o + bj * 32 + 4) = v1; }
;                     else *(u32x4*)(xo + bj * 32) = pack8(v0, v1);
;                     ss += (v0[0] * v0[0] + v0[1] * v0[1]) + (v0[2] * v0[2] + v0[3] * v0[3]) + (v1[0] * v1[0] + v1[1] * v1[1]) + (v1[2] * v1[2] + v1[3] * v1[3]);
;                 }
;                 ss = fq_sum(ss);
;                 if (fq == 0) ssx[(size_t)row * 32 + u.pn * 4 + wc] = ss;
.LBB0_661:
	s_or_b64 exec, exec, s[16:17]
	ds_read_b32 v6, v146 offset:2752
	v_add_u32_e32 v2, 0xb0, v142
	v_ashrrev_i32_e32 v3, 31, v2
	s_waitcnt lgkmcnt(0)
	v_lshlrev_b64 v[4:5], 12, v[2:3]
	v_lshl_add_u64 v[4:5], s[54:55], 0, v[4:5]
	v_pk_mul_f32 v[8:9], v[52:53], v[6:7] op_sel_hi:[1,0]
	v_pk_mul_f32 v[12:13], v[50:51], v[6:7] op_sel_hi:[1,0]
	v_lshl_add_u64 v[10:11], v[140:141], 1, v[4:5]
	v_pk_mul_f32 v[14:15], v[64:65], v[6:7] op_sel_hi:[1,0]
	v_pk_mul_f32 v[16:17], v[62:63], v[6:7] op_sel_hi:[1,0]
	v_cvt_pk_bf16_f32 v5, v8, v9
	v_mul_f32_e32 v7, v13, v13
	v_mul_f32_e32 v9, v9, v9
	v_fmac_f32_e32 v7, v12, v12
	v_fmac_f32_e32 v9, v8, v8
	v_mul_f32_e32 v8, v17, v17
	v_add_f32_e32 v7, v7, v9
	v_fmac_f32_e32 v8, v16, v16
	v_add_f32_e32 v7, v8, v7
	v_mul_f32_e32 v8, v15, v15
	v_fmac_f32_e32 v8, v14, v14
	v_add_f32_e32 v7, v8, v7
	v_cvt_pk_bf16_f32 v4, v12, v13
	v_pk_mul_f32 v[8:9], v[48:49], v[6:7] op_sel_hi:[1,0]
	v_pk_mul_f32 v[12:13], v[46:47], v[6:7] op_sel_hi:[1,0]
	v_pk_mul_f32 v[18:19], v[60:61], v[6:7] op_sel_hi:[1,0]
	v_pk_mul_f32 v[20:21], v[58:59], v[6:7] op_sel_hi:[1,0]
	v_mul_f32_e32 v6, v13, v13
	v_mul_f32_e32 v22, v9, v9
	v_fmac_f32_e32 v6, v12, v12
	v_fmac_f32_e32 v22, v8, v8
	v_add_f32_e32 v6, v6, v22
	v_mul_f32_e32 v22, v21, v21
	v_fmac_f32_e32 v22, v20, v20
	v_add_f32_e32 v6, v22, v6
	v_mul_f32_e32 v22, v19, v19
	v_fmac_f32_e32 v22, v18, v18
	v_add_f32_e32 v6, v22, v6
	v_add_f32_e32 v22, v7, v6
	ds_bpermute_b32 v23, v145, v22
	v_cvt_pk_bf16_f32 v6, v16, v17
	v_cvt_pk_bf16_f32 v7, v14, v15
	ds_write_b128 v161, v[4:7]
	s_waitcnt lgkmcnt(0)
	s_nop 0
	v_add_f32_e32 v4, v22, v23
	ds_bpermute_b32 v5, v144, v4
	v_cvt_pk_bf16_f32 v6, v12, v13
	v_cvt_pk_bf16_f32 v7, v8, v9
	v_cvt_pk_bf16_f32 v8, v20, v21
	v_cvt_pk_bf16_f32 v9, v18, v19
	ds_write_b128 v161, v[6:9] offset:64
	ds_read_b128 v[168:171], v160
	ds_read_b128 v[172:175], v160 offset:1152
	v_lshl_add_u64 v[166:167], v[10:11], 0, v[162:163]
	s_waitcnt lgkmcnt(0)
	global_store_dwordx4 v[166:167], v[168:171], off
	v_lshl_add_u64 v[166:167], v[166:167], 0, s[4:5]
	s_nop 0
	global_store_dwordx4 v[166:167], v[172:175], off
	s_and_saveexec_b64 s[16:17], s[40:41]
	s_cbranch_execz .LBB0_663
	v_lshlrev_b64 v[2:3], 7, v[2:3]
	v_lshl_add_u64 v[2:3], s[56:57], 0, v[2:3]
	v_lshl_add_u64 v[2:3], s[14:15], 2, v[2:3]
	s_lshl_b32 s44, s95, 2
	s_waitcnt lgkmcnt(0)
	v_add_f32_e32 v4, v4, v5
	v_lshl_add_u64 v[2:3], v[2:3], 0, s[44:45]
	global_store_dword v[2:3], v4, off
.LBB0_663:
	s_or_b64 exec, exec, s[16:17]
	s_andn2_b64 vcc, exec, s[42:43]
	s_mov_b64 s[14:15], -1
	s_cbranch_vccnz .LBB0_634
	s_lshl_b32 s1, s8, 8
	v_add_u32_e32 v66, s1, v154
	v_lshl_add_u32 v2, s0, 8, v193
	v_ashrrev_i32_e32 v67, 31, v66
	s_waitcnt lgkmcnt(0)
	v_lshlrev_b64 v[4:5], 12, v[66:67]
	v_ashrrev_i32_e32 v3, 31, v2
	v_lshl_add_u64 v[4:5], s[54:55], 0, v[4:5]
	v_lshl_add_u64 v[2:3], v[2:3], 1, v[4:5]
	s_mov_b64 s[4:5], 0x10000
	v_lshl_add_u64 v[4:5], v[2:3], 0, s[4:5]
	s_mov_b32 s4, 0x10000
	v_add_co_u32_e32 v6, vcc, s4, v2
	s_mov_b64 s[4:5], 0x20000
	s_nop 0
	v_addc_co_u32_e32 v7, vcc, 0, v3, vcc
	v_lshl_add_u64 v[4:5], v[2:3], 0, s[4:5]
	s_mov_b32 s4, 0x20000
	v_add_co_u32_e32 v6, vcc, s4, v2
	s_mov_b64 s[4:5], 0x30000
	s_nop 0
	v_addc_co_u32_e32 v7, vcc, 0, v3, vcc
	v_lshl_add_u64 v[4:5], v[2:3], 0, s[4:5]
	s_mov_b32 s4, 0x30000
	v_add_co_u32_e32 v6, vcc, s4, v2
	s_mov_b64 s[4:5], 0x80000
	s_nop 0
	v_addc_co_u32_e32 v7, vcc, 0, v3, vcc
	v_lshl_add_u64 v[4:5], v[2:3], 0, s[4:5]
	s_mov_b32 s4, 0x80000
	v_add_co_u32_e32 v6, vcc, s4, v2
	s_mov_b64 s[4:5], 0x90000
	s_nop 0
	v_addc_co_u32_e32 v7, vcc, 0, v3, vcc
	v_lshl_add_u64 v[4:5], v[2:3], 0, s[4:5]
	s_mov_b32 s4, 0x90000
	v_add_co_u32_e32 v6, vcc, s4, v2
	s_mov_b64 s[4:5], 0xa0000
	s_nop 0
	v_addc_co_u32_e32 v7, vcc, 0, v3, vcc
	v_lshl_add_u64 v[4:5], v[2:3], 0, s[4:5]
	s_mov_b32 s4, 0xa0000
	v_add_co_u32_e32 v6, vcc, s4, v2
	s_mov_b32 s4, 0xb0000
	s_nop 0
	v_addc_co_u32_e32 v7, vcc, 0, v3, vcc
	v_lshl_add_u64 v[4:5], v[2:3], 0, s[74:75]
	v_add_co_u32_e32 v2, vcc, s4, v2
	s_mul_i32 s9, s34, 0xc00
	s_nop 0
	v_addc_co_u32_e32 v3, vcc, 0, v3, vcc
	s_nop 0
	v_subrev_u32_e32 v66, s1, v66
	s_add_i32 s1, s9, 0
	v_lshl_add_u32 v66, v66, 2, s1
	v_add_u32_e32 v66, 0x20000, v66
	s_waitcnt vmcnt(16)
	v_mov_b64_e32 v[2:3], v[176:177]
	v_mov_b64_e32 v[4:5], v[178:179]
	v_mov_b64_e32 v[6:7], v[180:181]
	v_mov_b64_e32 v[8:9], v[182:183]
	v_mov_b64_e32 v[10:11], v[194:195]
	v_mov_b64_e32 v[12:13], v[196:197]
	v_mov_b64_e32 v[14:15], v[198:199]
	v_mov_b64_e32 v[16:17], v[200:201]
	v_mov_b64_e32 v[18:19], v[202:203]
	v_mov_b64_e32 v[20:21], v[204:205]
	v_mov_b64_e32 v[22:23], v[206:207]
	v_mov_b64_e32 v[24:25], v[208:209]
	v_mov_b64_e32 v[26:27], v[210:211]
	v_mov_b64_e32 v[28:29], v[212:213]
	v_mov_b64_e32 v[30:31], v[214:215]
	v_mov_b64_e32 v[32:33], v[216:217]
	v_mov_b64_e32 v[34:35], v[218:219]
	v_mov_b64_e32 v[36:37], v[220:221]
	v_mov_b64_e32 v[38:39], v[222:223]
	v_mov_b64_e32 v[40:41], v[224:225]
	v_mov_b64_e32 v[42:43], v[226:227]
	v_mov_b64_e32 v[44:45], v[228:229]
	v_mov_b64_e32 v[46:47], v[230:231]
	v_mov_b64_e32 v[48:49], v[232:233]
	v_mov_b64_e32 v[50:51], v[234:235]
	v_mov_b64_e32 v[52:53], v[236:237]
	v_mov_b64_e32 v[54:55], v[238:239]
	v_mov_b64_e32 v[56:57], v[240:241]
	v_mov_b64_e32 v[58:59], v[242:243]
	v_mov_b64_e32 v[60:61], v[244:245]
	v_mov_b64_e32 v[62:63], v[246:247]
	v_mov_b64_e32 v[64:65], v[248:249]
	ds_read2_b32 v[100:101], v66 offset1:16
	ds_read2_b32 v[84:85], v66 offset0:32 offset1:48
	ds_read2_b32 v[68:69], v66 offset0:128 offset1:144
	ds_read2_b32 v[74:75], v66 offset0:160 offset1:176
	v_readlane_b32 s4, v255, 15
	v_readlane_b32 s5, v255, 16
	s_waitcnt lgkmcnt(0)
	v_mov_b32_e32 v98, v101
	v_mov_b32_e32 v70, v85
	v_mov_b32_e32 v66, v69
	s_and_b64 vcc, exec, s[4:5]
	v_mov_b32_e32 v140, v75
	s_cbranch_vccnz .LBB0_633
	s_barrier
	s_branch .LBB0_633
